# lever 7 instruction selection: the moba block-selection loop exchanges its partial dot product between the wave halves with v_permlane32_swap instead of an LDS ds_bpermute round trip (same sum)
# speedup vs baseline: 1.0067x; 1.0065x over previous
.LBB0_589:
	ds_read_b128 v[44:47], v1
	ds_read_b128 v[48:51], v1 offset:16
	ds_read_b128 v[52:55], v1 offset:64
	ds_read_b128 v[56:59], v1 offset:80
	ds_read_b128 v[60:63], v1 offset:128
	s_waitcnt lgkmcnt(4)
	v_fma_f32 v43, v44, v15, 0
	v_fmac_f32_e32 v43, v45, v16
	v_fmac_f32_e32 v43, v46, v17
	v_fmac_f32_e32 v43, v47, v18
	s_waitcnt lgkmcnt(3)
	v_fmac_f32_e32 v43, v48, v19
	v_fmac_f32_e32 v43, v49, v20
	v_fmac_f32_e32 v43, v50, v21
	v_fmac_f32_e32 v43, v51, v22
	s_waitcnt lgkmcnt(2)
	v_fmac_f32_e32 v43, v52, v23
	v_fmac_f32_e32 v43, v53, v24
	v_fmac_f32_e32 v43, v54, v25
	v_fmac_f32_e32 v43, v55, v26
	s_waitcnt lgkmcnt(1)
	v_fmac_f32_e32 v43, v56, v27
	v_fmac_f32_e32 v43, v57, v28
	v_fmac_f32_e32 v43, v58, v29
	ds_read_b128 v[44:47], v1 offset:144
	ds_read_b128 v[48:51], v1 offset:192
	v_fmac_f32_e32 v43, v59, v30
	s_waitcnt lgkmcnt(2)
	v_fmac_f32_e32 v43, v60, v31
	v_fmac_f32_e32 v43, v61, v32
	v_fmac_f32_e32 v43, v62, v35
	v_fmac_f32_e32 v43, v63, v37
	s_waitcnt lgkmcnt(1)
	v_pk_mul_f32 v[44:45], v[44:45], v[2:3]
	s_waitcnt lgkmcnt(0)
	v_pk_mul_f32 v[48:49], v[48:49], v[6:7]
	v_add_f32_e32 v43, v43, v44
	v_add_f32_e32 v43, v45, v43
	v_pk_mul_f32 v[44:45], v[46:47], v[4:5]
	s_nop 0
	v_add_f32_e32 v43, v43, v44
	v_add_f32_e32 v43, v45, v43
	ds_read_b128 v[44:47], v1 offset:208
	v_add_f32_e32 v43, v43, v48
	v_add_f32_e32 v43, v49, v43
	v_pk_mul_f32 v[48:49], v[50:51], v[8:9]
	s_waitcnt lgkmcnt(0)
	v_pk_mul_f32 v[44:45], v[44:45], v[10:11]
	v_add_f32_e32 v43, v43, v48
	v_add_f32_e32 v43, v49, v43
	v_add_f32_e32 v43, v43, v44
	v_add_f32_e32 v43, v45, v43
	v_pk_mul_f32 v[44:45], v[46:47], v[12:13]
	v_mov_b32_e32 v46, v39
	v_add_f32_e32 v43, v43, v44
	v_add_f32_e32 v43, v45, v43
	v_mov_b32_e32 v44, v43
	v_mov_b32_e32 v45, s11
	s_nop 1
	v_permlane32_swap_b32_e32 v44, v43
	v_add_f32_e32 v44, v43, v44
	v_cmp_ngt_f32_e32 vcc, v44, v39
	v_mov_b32_e32 v43, v36
	s_and_saveexec_b64 s[4:5], vcc
	s_cbranch_execz .LBB0_595
	v_cmp_ngt_f32_e32 vcc, v44, v40
	v_mov_b32_e32 v43, s11
	s_and_saveexec_b64 s[6:7], vcc
	s_cbranch_execz .LBB0_594
	v_cmp_gt_f32_e32 vcc, v44, v42
	s_and_saveexec_b64 s[8:9], vcc
	v_mov_b32_e32 v38, s11
	v_mov_b32_e32 v42, v44
	s_or_b64 exec, exec, s[8:9]
	v_mov_b32_e32 v44, v40
	v_mov_b32_e32 v40, v42
	v_mov_b32_e32 v43, v41
	v_mov_b32_e32 v41, v38
